# attention key-tile order: diagonal tiles backwards, then unmasked tiles ascending from tile 0 (tasks of one head read the same tile together); on top of v96
# baseline (speedup 1.0000x reference)
.LBB0_506:
	s_or_b64 exec, exec, s[4:5]
	s_sub_i32 s57, s15, 16
	s_andn2_b32 s57, s57, 0xff
	s_cmp_gt_u32 s12, s57
	s_cselect_b32 s4, 0xffffffc0, 64
	s_add_i32 s4, s12, s4
	s_cmp_eq_u32 s12, s57
	s_cselect_b32 s12, 0, s4
	s_cmp_gt_u32 s12, s57
	s_cselect_b32 s4, 0xffffffc0, 64
	s_add_i32 s4, s12, s4
	s_cmp_eq_u32 s12, s57
	s_cselect_b32 s4, 0, s4
	s_add_i32 s4, s4, 64
	s_mov_b32 s5, 0
	s_sub_i32 s57, s57, 64
	s_max_i32 s57, s57, 0
	s_add_i32 s64, s64, 1
	v_lshl_add_u64 v[138:139], s[4:5], 2, v[164:165]
	v_add_u32_e32 v65, s4, v190
	v_mov_b32_e32 v140, s33
	v_cmp_lt_i32_e32 vcc, 15, v65
	v_min_i32_e32 v64, 0x80f, v65
	s_nop 0
	v_cndmask_b32_e32 v65, v179, v140, vcc
	v_add_u32_e32 v66, v65, v64
	v_ashrrev_i32_e32 v67, 31, v66
	v_lshlrev_b64 v[66:67], 14, v[66:67]
	v_lshl_add_u64 v[66:67], v[160:161], 0, v[66:67]
	v_add_co_u32_e32 v72, vcc, s65, v66
	v_ashrrev_i32_e32 v65, 31, v64
	s_nop 0
	v_addc_co_u32_e32 v73, vcc, 0, v67, vcc
	v_add_co_u32_e32 v74, vcc, s63, v66
	v_lshl_add_u64 v[134:135], v[64:65], 2, s[54:55]
	s_nop 0
	v_addc_co_u32_e32 v75, vcc, 0, v67, vcc
	v_add_u32_e32 v67, s4, v189
	v_cmp_lt_i32_e32 vcc, 15, v67
	v_min_i32_e32 v66, 0x80f, v67
	s_nop 0
	v_cndmask_b32_e32 v67, v179, v140, vcc
	v_add_u32_e32 v68, v67, v66
	v_ashrrev_i32_e32 v69, 31, v68
	v_lshlrev_b64 v[68:69], 14, v[68:69]
	v_lshl_add_u64 v[68:69], v[160:161], 0, v[68:69]
	v_add_co_u32_e32 v76, vcc, 0x2000, v68
	v_ashrrev_i32_e32 v67, 31, v66
	s_nop 0
	v_addc_co_u32_e32 v77, vcc, 0, v69, vcc
	v_add_co_u32_e32 v78, vcc, 0x3000, v68
	v_lshl_add_u64 v[136:137], v[66:67], 2, s[54:55]
	s_nop 0
	v_addc_co_u32_e32 v79, vcc, 0, v69, vcc
	s_waitcnt vmcnt(5)
	v_lshlrev_b32_e32 v64, 16, v130
	v_and_b32_e32 v65, 0xffff0000, v130
	v_lshlrev_b32_e32 v66, 16, v131
	v_and_b32_e32 v67, 0xffff0000, v131
	s_waitcnt vmcnt(3)
	v_pk_mul_f32 v[64:65], v[168:169], v[64:65] op_sel_hi:[0,1]
	v_pk_mul_f32 v[66:67], v[168:169], v[66:67] op_sel_hi:[0,1]
	v_cvt_pk_bf16_f32 v64, v64, v65
	v_cvt_pk_bf16_f32 v65, v66, v67
	v_lshlrev_b32_e32 v66, 16, v132
	v_and_b32_e32 v67, 0xffff0000, v132
	v_lshlrev_b32_e32 v68, 16, v133
	v_and_b32_e32 v69, 0xffff0000, v133
	v_add_u32_e32 v70, s56, v128
	v_pk_mul_f32 v[66:67], v[168:169], v[66:67] op_sel_hi:[0,1]
	v_pk_mul_f32 v[68:69], v[168:169], v[68:69] op_sel_hi:[0,1]
	v_cvt_pk_bf16_f32 v66, v66, v67
	v_cvt_pk_bf16_f32 v67, v68, v69
	v_add_u32_e32 v68, v70, v174
	ds_write_b128 v68, v[64:67]
	v_add_u32_e32 v71, s56, v248
	ds_write_b128 v71, v[116:119] offset:17408
	s_waitcnt vmcnt(2)
	v_lshlrev_b32_e32 v64, 16, v120
	v_and_b32_e32 v65, 0xffff0000, v120
	v_lshlrev_b32_e32 v66, 16, v121
	v_and_b32_e32 v67, 0xffff0000, v121
	s_waitcnt vmcnt(0)
	v_pk_mul_f32 v[64:65], v[166:167], v[64:65] op_sel_hi:[0,1]
	v_pk_mul_f32 v[66:67], v[166:167], v[66:67] op_sel_hi:[0,1]
	v_cvt_pk_bf16_f32 v64, v64, v65
	v_cvt_pk_bf16_f32 v65, v66, v67
	v_lshlrev_b32_e32 v66, 16, v122
	v_and_b32_e32 v67, 0xffff0000, v122
	v_lshlrev_b32_e32 v68, 16, v123
	v_and_b32_e32 v69, 0xffff0000, v123
	v_pk_mul_f32 v[66:67], v[166:167], v[66:67] op_sel_hi:[0,1]
	v_pk_mul_f32 v[68:69], v[166:167], v[68:69] op_sel_hi:[0,1]
	v_cvt_pk_bf16_f32 v66, v66, v67
	v_cvt_pk_bf16_f32 v67, v68, v69
	v_add_u32_e32 v68, v70, v175
	s_cmp_eq_u32 s12, s57
	ds_write_b128 v68, v[64:67]
	ds_write_b128 v71, v[124:127] offset:25600
	s_cbranch_scc1 .Lld_skip
	s_and_saveexec_b64 s[4:5], s[0:1]
	s_cbranch_execz .Llde_b
	global_load_dwordx4 v[112:115], v[138:139], off offset:-256

.Lld_skip:
	s_waitcnt lgkmcnt(0)
	s_barrier
	s_cmp_eq_u32 s12, s57
	s_cbranch_scc1 .LBB0_568
